# E2A conv unit: 43-iteration in-place conv loop software-pipelined (next 3 rows prefetched into v242-v253, single base address with +-2048 immediates), on top of v42
# speedup vs baseline: 1.0102x; 1.0102x over previous
; __device__ __forceinline__ float bflo(unsigned v) { return __uint_as_float(v << 16); }
; __device__ __forceinline__ float bfhi(unsigned v) { return __uint_as_float(v & 0xffff0000u); }
; __device__ __forceinline__ void conv_unit(const Params& p, const WS& ws, int j, int u) {
;     ...
;   bf16_t* xp = ws.XA + (size_t)(b * T_) * 1024 + cbase;
;   float x0[8], x1[8], x2[8];
;   {
;     u32x4 h[3];
; #pragma unroll
;     for (int m = 0; m < 3; ++m) {
;       const int t = t0 - 3 + m;
;       h[m] = (u32x4){0, 0, 0, 0};
;       if (t >= 0) h[m] = *(const u32x4*)(xp + (size_t)t * 1024);
;     }
;     const u32x4 a = h[0], bq = h[1], c = h[2];
;     x0[0] = bflo(a.x); x0[1] = bfhi(a.x); x0[2] = bflo(a.y); x0[3] = bfhi(a.y); x0[4] = bflo(a.z); x0[5] = bfhi(a.z); x0[6] = bflo(a.w); x0[7] = bfhi(a.w);
;     x1[0] = bflo(bq.x); x1[1] = bfhi(bq.x); x1[2] = bflo(bq.y); x1[3] = bfhi(bq.y); x1[4] = bflo(bq.z); x1[5] = bfhi(bq.z); x1[6] = bflo(bq.w); x1[7] = bfhi(bq.w);
;     x2[0] = bflo(c.x); x2[1] = bfhi(c.x); x2[2] = bflo(c.y); x2[3] = bfhi(c.y); x2[4] = bflo(c.z); x2[5] = bfhi(c.z); x2[6] = bflo(c.w); x2[7] = bfhi(c.w);
;   }
;   __syncthreads();
; #pragma unroll 1
;   for (int tt = 0; tt < 129; tt += 3) {
;     u32x4 r[3];
; #pragma unroll
;     for (int m = 0; m < 3; ++m) r[m] = *(const u32x4*)(xp + (size_t)(t0 + tt + m) * 1024);
; #pragma unroll
;     for (int m = 0; m < 3; ++m) {
;       float x3[8];
;       x3[0] = bflo(r[m].x); x3[1] = bfhi(r[m].x); x3[2] = bflo(r[m].y); x3[3] = bfhi(r[m].y);
;       x3[4] = bflo(r[m].z); x3[5] = bfhi(r[m].z); x3[6] = bflo(r[m].w); x3[7] = bfhi(r[m].w);
;       float y[8];
; #pragma unroll
;       for (int e = 0; e < 8; ++e) y[e] = cb[e] + cw[0][e] * x0[e] + cw[1][e] * x1[e] + cw[2][e] * x2[e] + cw[3][e] * x3[e];
;       u32x4 pk; pk.x = cvt_pk_bf16(y[0], y[1]); pk.y = cvt_pk_bf16(y[2], y[3]); pk.z = cvt_pk_bf16(y[4], y[5]); pk.w = cvt_pk_bf16(y[6], y[7]);
;       *(u32x4*)(xp + (size_t)(t0 + tt + m) * 1024) = pk;
; #pragma unroll
;       for (int e = 0; e < 8; ++e) { x0[e] = x1[e]; x1[e] = x2[e]; x2[e] = x3[e]; }
;     }
;   }
.LBB0_1235:
	s_or_b64 exec, exec, s[4:5]
	s_lshr_b32 s4, s70, 3
	s_waitcnt vmcnt(0)
	v_lshlrev_b32_e32 v64, 16, v42
	v_and_b32_e32 v65, 0xffff0000, v42
	v_add_u32_e32 v42, 2, v54
	s_mul_i32 s92, s4, 0x204000
	v_lshlrev_b32_e32 v72, 16, v43
	v_and_b32_e32 v73, 0xffff0000, v43
	v_ashrrev_i32_e32 v43, 31, v42
	s_lshl_b32 s8, s71, 1
	s_lshl_b64 s[4:5], s[92:93], 1
	v_lshlrev_b64 v[42:43], 11, v[42:43]
	s_and_b32 s8, s8, 0x700
	v_lshl_add_u64 v[42:43], v[42:43], 0, s[4:5]
	v_lshl_or_b32 v13, v13, 1, s8
	v_or_b32_e32 v42, v42, v13
	v_lshlrev_b32_e32 v62, 16, v50
	v_and_b32_e32 v63, 0xffff0000, v50
	v_lshlrev_b32_e32 v68, 16, v51
	v_and_b32_e32 v69, 0xffff0000, v51
	v_lshl_add_u64 v[50:51], s[50:51], 0, v[42:43]
	v_add_u32_e32 v42, 1, v54
	v_ashrrev_i32_e32 v43, 31, v42
	v_lshlrev_b64 v[42:43], 11, v[42:43]
	v_lshl_add_u64 v[42:43], v[42:43], 0, s[4:5]
	v_or_b32_e32 v42, v42, v13
	v_ashrrev_i32_e32 v55, 31, v54
	v_lshlrev_b32_e32 v80, 16, v52
	v_and_b32_e32 v81, 0xffff0000, v52
	v_lshlrev_b32_e32 v66, 16, v53
	v_and_b32_e32 v67, 0xffff0000, v53
	v_lshl_add_u64 v[52:53], s[50:51], 0, v[42:43]
	v_lshlrev_b64 v[42:43], 11, v[54:55]
	v_lshl_add_u64 v[42:43], v[42:43], 0, s[4:5]
	v_or_b32_e32 v42, v42, v13
	v_lshlrev_b32_e32 v78, 16, v46
	v_and_b32_e32 v79, 0xffff0000, v46
	v_lshlrev_b32_e32 v74, 16, v47
	v_and_b32_e32 v75, 0xffff0000, v47
	v_lshlrev_b32_e32 v84, 16, v48
	v_and_b32_e32 v85, 0xffff0000, v48
	v_lshlrev_b32_e32 v82, 16, v44
	v_and_b32_e32 v83, 0xffff0000, v44
	v_lshlrev_b32_e32 v76, 16, v49
	v_and_b32_e32 v77, 0xffff0000, v49
	v_lshlrev_b32_e32 v70, 16, v45
	v_and_b32_e32 v71, 0xffff0000, v45
	v_lshl_add_u64 v[54:55], s[50:51], 0, v[42:43]
	s_mov_b32 s4, -3
	s_barrier
	global_load_dwordx4 v[242:245], v[52:53], off offset:-2048
	global_load_dwordx4 v[246:249], v[52:53], off
	global_load_dwordx4 v[250:253], v[52:53], off offset:2048
	s_waitcnt vmcnt(0)
	s_branch .Lconv_body
.LBB0_1236:
	s_waitcnt vmcnt(3)
.Lconv_body:
	v_mov_b32_e32 v86, v242
	v_mov_b32_e32 v87, v243
	v_mov_b32_e32 v88, v244
	v_mov_b32_e32 v89, v245
	v_mov_b32_e32 v46, v246
	v_mov_b32_e32 v47, v247
	v_mov_b32_e32 v48, v248
	v_mov_b32_e32 v49, v249
	v_mov_b32_e32 v42, v250
	v_mov_b32_e32 v43, v251
	v_mov_b32_e32 v44, v252
	v_mov_b32_e32 v45, v253
	v_lshl_add_u64 v[54:55], v[52:53], 0, s[90:91]
	global_load_dwordx4 v[242:245], v[54:55], off offset:-2048
	global_load_dwordx4 v[246:249], v[54:55], off
	global_load_dwordx4 v[250:253], v[54:55], off offset:2048
	v_pk_fma_f32 v[58:59], v[14:15], v[78:79], v[4:5]
	v_pk_fma_f32 v[60:61], v[14:15], v[64:65], v[4:5]
	v_pk_fma_f32 v[58:59], v[22:23], v[64:65], v[58:59]
	v_pk_fma_f32 v[60:61], v[22:23], v[62:63], v[60:61]
	v_pk_fma_f32 v[58:59], v[30:31], v[62:63], v[58:59]
	v_pk_fma_f32 v[62:63], v[14:15], v[62:63], v[4:5]
	v_pk_fma_f32 v[74:75], v[16:17], v[74:75], v[6:7]
	v_pk_fma_f32 v[78:79], v[8:9], v[82:83], v[0:1]
	v_pk_fma_f32 v[74:75], v[24:25], v[72:73], v[74:75]
	v_pk_fma_f32 v[72:73], v[16:17], v[72:73], v[6:7]
	v_pk_fma_f32 v[74:75], v[32:33], v[68:69], v[74:75]
	v_pk_fma_f32 v[72:73], v[24:25], v[68:69], v[72:73]
	v_pk_fma_f32 v[68:69], v[16:17], v[68:69], v[6:7]
	v_pk_fma_f32 v[78:79], v[18:19], v[80:81], v[78:79]
	v_pk_fma_f32 v[76:77], v[10:11], v[76:77], v[2:3]
	s_add_i32 s4, s4, 3
	v_pk_fma_f32 v[76:77], v[20:21], v[70:71], v[76:77]
	v_pk_fma_f32 v[70:71], v[10:11], v[70:71], v[2:3]
	v_pk_fma_f32 v[76:77], v[28:29], v[66:67], v[76:77]
	v_pk_fma_f32 v[70:71], v[20:21], v[66:67], v[70:71]
	v_pk_fma_f32 v[66:67], v[10:11], v[66:67], v[2:3]
	s_cmpk_lt_u32 s4, 0x7e
	v_lshlrev_b32_e32 v56, 16, v86
	v_and_b32_e32 v57, 0xffff0000, v86
	v_pk_fma_f32 v[58:59], v[38:39], v[56:57], v[58:59]
	v_pk_fma_f32 v[60:61], v[30:31], v[56:57], v[60:61]
	v_cvt_pk_bf16_f32 v86, v58, v59
	v_lshlrev_b32_e32 v58, 16, v46
	v_and_b32_e32 v59, 0xffff0000, v46
	v_pk_fma_f32 v[60:61], v[38:39], v[58:59], v[60:61]
	v_pk_fma_f32 v[62:63], v[22:23], v[56:57], v[62:63]
	v_cvt_pk_bf16_f32 v90, v60, v61
	v_lshlrev_b32_e32 v60, 16, v42
	v_and_b32_e32 v61, 0xffff0000, v42
	v_pk_fma_f32 v[62:63], v[30:31], v[58:59], v[62:63]
	v_lshlrev_b32_e32 v46, 16, v47
	v_pk_fma_f32 v[64:65], v[38:39], v[60:61], v[62:63]
	v_lshlrev_b32_e32 v62, 16, v87
	v_and_b32_e32 v63, 0xffff0000, v87
	v_pk_fma_f32 v[74:75], v[40:41], v[62:63], v[74:75]
	v_and_b32_e32 v47, 0xffff0000, v47
	v_cvt_pk_bf16_f32 v87, v74, v75
	v_pk_fma_f32 v[72:73], v[32:33], v[62:63], v[72:73]
	v_pk_fma_f32 v[68:69], v[24:25], v[62:63], v[68:69]
	v_pk_fma_f32 v[74:75], v[8:9], v[84:85], v[0:1]
	v_pk_fma_f32 v[72:73], v[40:41], v[46:47], v[72:73]
	v_lshlrev_b32_e32 v42, 16, v43
	v_and_b32_e32 v43, 0xffff0000, v43
	v_pk_fma_f32 v[68:69], v[32:33], v[46:47], v[68:69]
	v_pk_fma_f32 v[74:75], v[18:19], v[82:83], v[74:75]
	v_cvt_pk_bf16_f32 v91, v72, v73
	v_pk_fma_f32 v[72:73], v[40:41], v[42:43], v[68:69]
	v_lshlrev_b32_e32 v68, 16, v88
	v_and_b32_e32 v69, 0xffff0000, v88
	v_pk_fma_f32 v[74:75], v[26:27], v[80:81], v[74:75]
	v_pk_fma_f32 v[78:79], v[26:27], v[68:69], v[78:79]
	v_pk_fma_f32 v[74:75], v[34:35], v[68:69], v[74:75]
	v_pk_fma_f32 v[80:81], v[8:9], v[80:81], v[0:1]
	v_cvt_pk_bf16_f32 v88, v74, v75
	v_lshlrev_b32_e32 v74, 16, v48
	v_and_b32_e32 v75, 0xffff0000, v48
	v_pk_fma_f32 v[78:79], v[34:35], v[74:75], v[78:79]
	v_pk_fma_f32 v[80:81], v[18:19], v[68:69], v[80:81]
	v_cvt_pk_bf16_f32 v92, v78, v79
	v_lshlrev_b32_e32 v78, 16, v44
	v_and_b32_e32 v79, 0xffff0000, v44
	v_pk_fma_f32 v[80:81], v[26:27], v[74:75], v[80:81]
	v_lshlrev_b32_e32 v48, 16, v49
	v_pk_fma_f32 v[82:83], v[34:35], v[78:79], v[80:81]
	v_lshlrev_b32_e32 v80, 16, v89
	v_and_b32_e32 v81, 0xffff0000, v89
	v_and_b32_e32 v49, 0xffff0000, v49
	v_pk_fma_f32 v[70:71], v[28:29], v[80:81], v[70:71]
	v_pk_fma_f32 v[66:67], v[20:21], v[80:81], v[66:67]
	v_pk_fma_f32 v[70:71], v[36:37], v[48:49], v[70:71]
	v_lshlrev_b32_e32 v44, 16, v45
	v_and_b32_e32 v45, 0xffff0000, v45
	v_pk_fma_f32 v[66:67], v[28:29], v[48:49], v[66:67]
	v_pk_fma_f32 v[76:77], v[36:37], v[80:81], v[76:77]
	v_cvt_pk_bf16_f32 v93, v70, v71
	v_pk_fma_f32 v[70:71], v[36:37], v[44:45], v[66:67]
	v_cvt_pk_bf16_f32 v89, v76, v77
	v_cvt_pk_bf16_f32 v64, v64, v65
	v_cvt_pk_bf16_f32 v65, v72, v73
	v_cvt_pk_bf16_f32 v66, v82, v83
	v_cvt_pk_bf16_f32 v67, v70, v71
	global_store_dwordx4 v[52:53], v[86:89], off offset:-2048
	global_store_dwordx4 v[52:53], v[90:93], off
	global_store_dwordx4 v[52:53], v[64:67], off offset:2048
	s_nop 2
	v_mov_b64_e32 v[52:53], v[54:55]
	v_mov_b64_e32 v[66:67], v[44:45]
	v_mov_b64_e32 v[70:71], v[48:49]
	v_mov_b64_e32 v[76:77], v[80:81]
	v_mov_b64_e32 v[84:85], v[68:69]
	v_mov_b64_e32 v[82:83], v[74:75]
	v_mov_b64_e32 v[80:81], v[78:79]
	v_mov_b64_e32 v[74:75], v[62:63]
	v_mov_b64_e32 v[72:73], v[46:47]
	v_mov_b64_e32 v[68:69], v[42:43]
	v_mov_b64_e32 v[78:79], v[56:57]
	v_mov_b64_e32 v[64:65], v[58:59]
	v_mov_b64_e32 v[62:63], v[60:61]
	s_cbranch_scc1 .LBB0_1236
	s_barrier
	s_mov_b64 s[4:5], 0
